# v26 + per-unit accumulator zeroing in all 10 GEMM phases done with 64 packed 64-bit moves instead of 128 v_mov_b32
# speedup vs baseline: 1.0066x; 1.0013x over previous
.LBB0_165:
	s_ashr_i32 s19, s18, 31
	s_lshl_b64 s[20:21], s[18:19], 19
	s_add_u32 s20, s57, s20
	s_addc_u32 s21, s62, s21
	s_and_b64 s[24:25], s[4:5], exec
	s_cselect_b32 s7, s21, s27
	s_cselect_b32 s19, s20, s26
	s_ashr_i32 s17, s16, 31
	s_lshl_b64 s[24:25], s[16:17], 19
	s_add_u32 s24, s3, s24
	s_addc_u32 s25, s22, s25
	s_and_b64 s[30:31], s[4:5], exec
	s_cselect_b32 s17, s25, s29
	s_cselect_b32 s50, s24, s28
	s_add_u32 s26, s26, 0x40080
	s_addc_u32 s27, s27, 0
	s_add_u32 s51, s28, 0x100
	s_addc_u32 s52, s29, 0
	s_mov_b32 s53, -2
	v_mov_b32_e32 v0, 0
	v_mov_b32_e32 v1, 0
	v_pk_mov_b32 v[2:3], v[0:1], v[0:1]
	v_pk_mov_b32 v[4:5], v[0:1], v[0:1]
	v_pk_mov_b32 v[6:7], v[0:1], v[0:1]
	v_pk_mov_b32 v[8:9], v[0:1], v[0:1]
	v_pk_mov_b32 v[10:11], v[0:1], v[0:1]
	v_pk_mov_b32 v[12:13], v[0:1], v[0:1]
	v_pk_mov_b32 v[14:15], v[0:1], v[0:1]
	v_pk_mov_b32 v[16:17], v[0:1], v[0:1]
	v_pk_mov_b32 v[18:19], v[0:1], v[0:1]
	v_pk_mov_b32 v[20:21], v[0:1], v[0:1]
	v_pk_mov_b32 v[22:23], v[0:1], v[0:1]
	v_pk_mov_b32 v[24:25], v[0:1], v[0:1]
	v_pk_mov_b32 v[26:27], v[0:1], v[0:1]
	v_pk_mov_b32 v[28:29], v[0:1], v[0:1]
	v_pk_mov_b32 v[30:31], v[0:1], v[0:1]
	v_pk_mov_b32 v[32:33], v[0:1], v[0:1]
	v_pk_mov_b32 v[34:35], v[0:1], v[0:1]
	v_pk_mov_b32 v[36:37], v[0:1], v[0:1]
	v_pk_mov_b32 v[38:39], v[0:1], v[0:1]
	v_pk_mov_b32 v[40:41], v[0:1], v[0:1]
	v_pk_mov_b32 v[42:43], v[0:1], v[0:1]
	v_pk_mov_b32 v[44:45], v[0:1], v[0:1]
	v_pk_mov_b32 v[46:47], v[0:1], v[0:1]
	v_pk_mov_b32 v[48:49], v[0:1], v[0:1]
	v_pk_mov_b32 v[50:51], v[0:1], v[0:1]
	v_pk_mov_b32 v[52:53], v[0:1], v[0:1]
	v_pk_mov_b32 v[54:55], v[0:1], v[0:1]
	v_pk_mov_b32 v[56:57], v[0:1], v[0:1]
	v_pk_mov_b32 v[58:59], v[0:1], v[0:1]
	v_pk_mov_b32 v[60:61], v[0:1], v[0:1]
	v_pk_mov_b32 v[62:63], v[0:1], v[0:1]
	v_pk_mov_b32 v[64:65], v[0:1], v[0:1]
	v_pk_mov_b32 v[66:67], v[0:1], v[0:1]
	v_pk_mov_b32 v[68:69], v[0:1], v[0:1]
	v_pk_mov_b32 v[70:71], v[0:1], v[0:1]
	v_pk_mov_b32 v[72:73], v[0:1], v[0:1]
	v_pk_mov_b32 v[74:75], v[0:1], v[0:1]
	v_pk_mov_b32 v[76:77], v[0:1], v[0:1]
	v_pk_mov_b32 v[78:79], v[0:1], v[0:1]
	v_pk_mov_b32 v[80:81], v[0:1], v[0:1]
	v_pk_mov_b32 v[82:83], v[0:1], v[0:1]
	v_pk_mov_b32 v[84:85], v[0:1], v[0:1]
	v_pk_mov_b32 v[86:87], v[0:1], v[0:1]
	v_pk_mov_b32 v[88:89], v[0:1], v[0:1]
	v_pk_mov_b32 v[90:91], v[0:1], v[0:1]
	v_pk_mov_b32 v[92:93], v[0:1], v[0:1]
	v_pk_mov_b32 v[94:95], v[0:1], v[0:1]
	v_pk_mov_b32 v[96:97], v[0:1], v[0:1]
	v_pk_mov_b32 v[98:99], v[0:1], v[0:1]
	v_pk_mov_b32 v[100:101], v[0:1], v[0:1]
	v_pk_mov_b32 v[102:103], v[0:1], v[0:1]
	v_pk_mov_b32 v[104:105], v[0:1], v[0:1]
	v_pk_mov_b32 v[106:107], v[0:1], v[0:1]
	v_pk_mov_b32 v[108:109], v[0:1], v[0:1]
	v_pk_mov_b32 v[110:111], v[0:1], v[0:1]
	v_pk_mov_b32 v[112:113], v[0:1], v[0:1]
	v_pk_mov_b32 v[114:115], v[0:1], v[0:1]
	v_pk_mov_b32 v[116:117], v[0:1], v[0:1]
	v_pk_mov_b32 v[118:119], v[0:1], v[0:1]
	v_pk_mov_b32 v[120:121], v[0:1], v[0:1]
	v_pk_mov_b32 v[122:123], v[0:1], v[0:1]
	v_pk_mov_b32 v[124:125], v[0:1], v[0:1]
	v_pk_mov_b32 v[126:127], v[0:1], v[0:1]

.LBB0_205:
	s_ashr_i32 s15, s14, 31
	s_lshl_b64 s[20:21], s[14:15], 19
	s_add_u32 s20, s81, s20
	s_addc_u32 s21, s47, s21
	s_and_b64 s[24:25], s[4:5], exec
	s_cselect_b32 s15, s21, s27
	s_cselect_b32 s49, s20, s26
	s_ashr_i32 s13, s12, 31
	s_lshl_b64 s[24:25], s[12:13], 19
	s_add_u32 s24, s57, s24
	s_addc_u32 s25, s62, s25
	s_and_b64 s[30:31], s[4:5], exec
	s_cselect_b32 s13, s25, s29
	s_cselect_b32 s50, s24, s28
	s_add_u32 s26, s26, 0x40080
	s_addc_u32 s27, s27, 0
	s_add_u32 s51, s28, 0x100
	s_addc_u32 s52, s29, 0
	s_mov_b32 s53, -2
	v_mov_b32_e32 v0, 0
	v_mov_b32_e32 v1, 0
	v_pk_mov_b32 v[2:3], v[0:1], v[0:1]
	v_pk_mov_b32 v[4:5], v[0:1], v[0:1]
	v_pk_mov_b32 v[6:7], v[0:1], v[0:1]
	v_pk_mov_b32 v[8:9], v[0:1], v[0:1]
	v_pk_mov_b32 v[10:11], v[0:1], v[0:1]
	v_pk_mov_b32 v[12:13], v[0:1], v[0:1]
	v_pk_mov_b32 v[14:15], v[0:1], v[0:1]
	v_pk_mov_b32 v[16:17], v[0:1], v[0:1]
	v_pk_mov_b32 v[18:19], v[0:1], v[0:1]
	v_pk_mov_b32 v[20:21], v[0:1], v[0:1]
	v_pk_mov_b32 v[22:23], v[0:1], v[0:1]
	v_pk_mov_b32 v[24:25], v[0:1], v[0:1]
	v_pk_mov_b32 v[26:27], v[0:1], v[0:1]
	v_pk_mov_b32 v[28:29], v[0:1], v[0:1]
	v_pk_mov_b32 v[30:31], v[0:1], v[0:1]
	v_pk_mov_b32 v[32:33], v[0:1], v[0:1]
	v_pk_mov_b32 v[34:35], v[0:1], v[0:1]
	v_pk_mov_b32 v[36:37], v[0:1], v[0:1]
	v_pk_mov_b32 v[38:39], v[0:1], v[0:1]
	v_pk_mov_b32 v[40:41], v[0:1], v[0:1]
	v_pk_mov_b32 v[42:43], v[0:1], v[0:1]
	v_pk_mov_b32 v[44:45], v[0:1], v[0:1]
	v_pk_mov_b32 v[46:47], v[0:1], v[0:1]
	v_pk_mov_b32 v[48:49], v[0:1], v[0:1]
	v_pk_mov_b32 v[50:51], v[0:1], v[0:1]
	v_pk_mov_b32 v[52:53], v[0:1], v[0:1]
	v_pk_mov_b32 v[54:55], v[0:1], v[0:1]
	v_pk_mov_b32 v[56:57], v[0:1], v[0:1]
	v_pk_mov_b32 v[58:59], v[0:1], v[0:1]
	v_pk_mov_b32 v[60:61], v[0:1], v[0:1]
	v_pk_mov_b32 v[62:63], v[0:1], v[0:1]
	v_pk_mov_b32 v[64:65], v[0:1], v[0:1]
	v_pk_mov_b32 v[66:67], v[0:1], v[0:1]
	v_pk_mov_b32 v[68:69], v[0:1], v[0:1]
	v_pk_mov_b32 v[70:71], v[0:1], v[0:1]
	v_pk_mov_b32 v[72:73], v[0:1], v[0:1]
	v_pk_mov_b32 v[74:75], v[0:1], v[0:1]
	v_pk_mov_b32 v[76:77], v[0:1], v[0:1]
	v_pk_mov_b32 v[78:79], v[0:1], v[0:1]
	v_pk_mov_b32 v[80:81], v[0:1], v[0:1]
	v_pk_mov_b32 v[82:83], v[0:1], v[0:1]
	v_pk_mov_b32 v[84:85], v[0:1], v[0:1]
	v_pk_mov_b32 v[86:87], v[0:1], v[0:1]
	v_pk_mov_b32 v[88:89], v[0:1], v[0:1]
	v_pk_mov_b32 v[90:91], v[0:1], v[0:1]
	v_pk_mov_b32 v[92:93], v[0:1], v[0:1]
	v_pk_mov_b32 v[94:95], v[0:1], v[0:1]
	v_pk_mov_b32 v[96:97], v[0:1], v[0:1]
	v_pk_mov_b32 v[98:99], v[0:1], v[0:1]
	v_pk_mov_b32 v[100:101], v[0:1], v[0:1]
	v_pk_mov_b32 v[102:103], v[0:1], v[0:1]
	v_pk_mov_b32 v[104:105], v[0:1], v[0:1]
	v_pk_mov_b32 v[106:107], v[0:1], v[0:1]
	v_pk_mov_b32 v[108:109], v[0:1], v[0:1]
	v_pk_mov_b32 v[110:111], v[0:1], v[0:1]
	v_pk_mov_b32 v[112:113], v[0:1], v[0:1]
	v_pk_mov_b32 v[114:115], v[0:1], v[0:1]
	v_pk_mov_b32 v[116:117], v[0:1], v[0:1]
	v_pk_mov_b32 v[118:119], v[0:1], v[0:1]
	v_pk_mov_b32 v[120:121], v[0:1], v[0:1]
	v_pk_mov_b32 v[122:123], v[0:1], v[0:1]
	v_pk_mov_b32 v[124:125], v[0:1], v[0:1]
	v_pk_mov_b32 v[126:127], v[0:1], v[0:1]

.LBB0_458:
	s_ashr_i32 s13, s12, 31
	s_lshl_b64 s[20:21], s[12:13], 20
	s_add_u32 s20, s3, s20
	s_addc_u32 s21, s22, s21
	s_and_b64 s[24:25], s[4:5], exec
	s_cselect_b32 s13, s21, s27
	s_cselect_b32 s50, s20, s26
	s_ashr_i32 s11, s10, 31
	s_lshl_b64 s[24:25], s[10:11], 20
	v_readlane_b32 s11, v234, 53
	s_add_u32 s24, s11, s24
	s_addc_u32 s25, s89, s25
	s_and_b64 s[30:31], s[4:5], exec
	s_cselect_b32 s11, s25, s29
	s_cselect_b32 s51, s24, s28
	s_add_u32 s26, s26, 0x80080
	s_addc_u32 s27, s27, 0
	s_add_u32 s52, s28, 0x100
	s_addc_u32 s53, s29, 0
	s_mov_b32 s54, -2
	v_mov_b32_e32 v0, 0
	v_mov_b32_e32 v1, 0
	v_pk_mov_b32 v[2:3], v[0:1], v[0:1]
	v_pk_mov_b32 v[4:5], v[0:1], v[0:1]
	v_pk_mov_b32 v[6:7], v[0:1], v[0:1]
	v_pk_mov_b32 v[8:9], v[0:1], v[0:1]
	v_pk_mov_b32 v[10:11], v[0:1], v[0:1]
	v_pk_mov_b32 v[12:13], v[0:1], v[0:1]
	v_pk_mov_b32 v[14:15], v[0:1], v[0:1]
	v_pk_mov_b32 v[16:17], v[0:1], v[0:1]
	v_pk_mov_b32 v[18:19], v[0:1], v[0:1]
	v_pk_mov_b32 v[20:21], v[0:1], v[0:1]
	v_pk_mov_b32 v[22:23], v[0:1], v[0:1]
	v_pk_mov_b32 v[24:25], v[0:1], v[0:1]
	v_pk_mov_b32 v[26:27], v[0:1], v[0:1]
	v_pk_mov_b32 v[28:29], v[0:1], v[0:1]
	v_pk_mov_b32 v[30:31], v[0:1], v[0:1]
	v_pk_mov_b32 v[32:33], v[0:1], v[0:1]
	v_pk_mov_b32 v[34:35], v[0:1], v[0:1]
	v_pk_mov_b32 v[36:37], v[0:1], v[0:1]
	v_pk_mov_b32 v[38:39], v[0:1], v[0:1]
	v_pk_mov_b32 v[40:41], v[0:1], v[0:1]
	v_pk_mov_b32 v[42:43], v[0:1], v[0:1]
	v_pk_mov_b32 v[44:45], v[0:1], v[0:1]
	v_pk_mov_b32 v[46:47], v[0:1], v[0:1]
	v_pk_mov_b32 v[48:49], v[0:1], v[0:1]
	v_pk_mov_b32 v[50:51], v[0:1], v[0:1]
	v_pk_mov_b32 v[52:53], v[0:1], v[0:1]
	v_pk_mov_b32 v[54:55], v[0:1], v[0:1]
	v_pk_mov_b32 v[56:57], v[0:1], v[0:1]
	v_pk_mov_b32 v[58:59], v[0:1], v[0:1]
	v_pk_mov_b32 v[60:61], v[0:1], v[0:1]
	v_pk_mov_b32 v[62:63], v[0:1], v[0:1]
	v_pk_mov_b32 v[64:65], v[0:1], v[0:1]
	v_pk_mov_b32 v[66:67], v[0:1], v[0:1]
	v_pk_mov_b32 v[68:69], v[0:1], v[0:1]
	v_pk_mov_b32 v[70:71], v[0:1], v[0:1]
	v_pk_mov_b32 v[72:73], v[0:1], v[0:1]
	v_pk_mov_b32 v[74:75], v[0:1], v[0:1]
	v_pk_mov_b32 v[76:77], v[0:1], v[0:1]
	v_pk_mov_b32 v[78:79], v[0:1], v[0:1]
	v_pk_mov_b32 v[80:81], v[0:1], v[0:1]
	v_pk_mov_b32 v[82:83], v[0:1], v[0:1]
	v_pk_mov_b32 v[84:85], v[0:1], v[0:1]
	v_pk_mov_b32 v[86:87], v[0:1], v[0:1]
	v_pk_mov_b32 v[88:89], v[0:1], v[0:1]
	v_pk_mov_b32 v[90:91], v[0:1], v[0:1]
	v_pk_mov_b32 v[92:93], v[0:1], v[0:1]
	v_pk_mov_b32 v[94:95], v[0:1], v[0:1]
	v_pk_mov_b32 v[96:97], v[0:1], v[0:1]
	v_pk_mov_b32 v[98:99], v[0:1], v[0:1]
	v_pk_mov_b32 v[100:101], v[0:1], v[0:1]
	v_pk_mov_b32 v[102:103], v[0:1], v[0:1]
	v_pk_mov_b32 v[104:105], v[0:1], v[0:1]
	v_pk_mov_b32 v[106:107], v[0:1], v[0:1]
	v_pk_mov_b32 v[108:109], v[0:1], v[0:1]
	v_pk_mov_b32 v[110:111], v[0:1], v[0:1]
	v_pk_mov_b32 v[112:113], v[0:1], v[0:1]
	v_pk_mov_b32 v[114:115], v[0:1], v[0:1]
	v_pk_mov_b32 v[116:117], v[0:1], v[0:1]
	v_pk_mov_b32 v[118:119], v[0:1], v[0:1]
	v_pk_mov_b32 v[120:121], v[0:1], v[0:1]
	v_pk_mov_b32 v[122:123], v[0:1], v[0:1]
	v_pk_mov_b32 v[124:125], v[0:1], v[0:1]
	v_pk_mov_b32 v[126:127], v[0:1], v[0:1]

.LBB0_584:
	s_ashr_i32 s21, s20, 31
	s_lshl_b64 s[24:25], s[20:21], 18
	s_add_u32 s24, s57, s24
	s_addc_u32 s25, s62, s25
	s_and_b64 s[26:27], s[4:5], exec
	s_cselect_b32 s21, s25, s31
	s_cselect_b32 s53, s24, s30
	s_ashr_i32 s15, s14, 31
	s_lshl_b64 s[26:27], s[14:15], 18
	v_readlane_b32 s15, v234, 45
	s_add_u32 s26, s15, s26
	v_readlane_b32 s15, v234, 46
	s_addc_u32 s27, s15, s27
	s_and_b64 s[36:37], s[4:5], exec
	s_cselect_b32 s15, s27, s35
	s_cselect_b32 s54, s26, s34
	s_add_u32 s30, s30, 0x20080
	s_addc_u32 s31, s31, 0
	s_add_u32 s55, s34, 0x100
	s_addc_u32 s63, s35, 0
	s_mov_b32 s64, -2
	v_mov_b32_e32 v32, 0
	v_mov_b32_e32 v33, 0
	v_pk_mov_b32 v[34:35], v[32:33], v[32:33]
	v_pk_mov_b32 v[36:37], v[32:33], v[32:33]
	v_pk_mov_b32 v[38:39], v[32:33], v[32:33]
	v_pk_mov_b32 v[40:41], v[32:33], v[32:33]
	v_pk_mov_b32 v[42:43], v[32:33], v[32:33]
	v_pk_mov_b32 v[44:45], v[32:33], v[32:33]
	v_pk_mov_b32 v[46:47], v[32:33], v[32:33]
	v_pk_mov_b32 v[48:49], v[32:33], v[32:33]
	v_pk_mov_b32 v[50:51], v[32:33], v[32:33]
	v_pk_mov_b32 v[52:53], v[32:33], v[32:33]
	v_pk_mov_b32 v[54:55], v[32:33], v[32:33]
	v_pk_mov_b32 v[56:57], v[32:33], v[32:33]
	v_pk_mov_b32 v[58:59], v[32:33], v[32:33]
	v_pk_mov_b32 v[60:61], v[32:33], v[32:33]
	v_pk_mov_b32 v[62:63], v[32:33], v[32:33]
	v_pk_mov_b32 v[64:65], v[32:33], v[32:33]
	v_pk_mov_b32 v[66:67], v[32:33], v[32:33]
	v_pk_mov_b32 v[68:69], v[32:33], v[32:33]
	v_pk_mov_b32 v[70:71], v[32:33], v[32:33]
	v_pk_mov_b32 v[72:73], v[32:33], v[32:33]
	v_pk_mov_b32 v[74:75], v[32:33], v[32:33]
	v_pk_mov_b32 v[76:77], v[32:33], v[32:33]
	v_pk_mov_b32 v[78:79], v[32:33], v[32:33]
	v_pk_mov_b32 v[80:81], v[32:33], v[32:33]
	v_pk_mov_b32 v[82:83], v[32:33], v[32:33]
	v_pk_mov_b32 v[84:85], v[32:33], v[32:33]
	v_pk_mov_b32 v[86:87], v[32:33], v[32:33]
	v_pk_mov_b32 v[88:89], v[32:33], v[32:33]
	v_pk_mov_b32 v[90:91], v[32:33], v[32:33]
	v_pk_mov_b32 v[92:93], v[32:33], v[32:33]
	v_pk_mov_b32 v[94:95], v[32:33], v[32:33]
	v_pk_mov_b32 v[96:97], v[32:33], v[32:33]
	v_pk_mov_b32 v[98:99], v[32:33], v[32:33]
	v_pk_mov_b32 v[100:101], v[32:33], v[32:33]
	v_pk_mov_b32 v[102:103], v[32:33], v[32:33]
	v_pk_mov_b32 v[104:105], v[32:33], v[32:33]
	v_pk_mov_b32 v[106:107], v[32:33], v[32:33]
	v_pk_mov_b32 v[108:109], v[32:33], v[32:33]
	v_pk_mov_b32 v[110:111], v[32:33], v[32:33]
	v_pk_mov_b32 v[112:113], v[32:33], v[32:33]
	v_pk_mov_b32 v[114:115], v[32:33], v[32:33]
	v_pk_mov_b32 v[116:117], v[32:33], v[32:33]
	v_pk_mov_b32 v[118:119], v[32:33], v[32:33]
	v_pk_mov_b32 v[120:121], v[32:33], v[32:33]
	v_pk_mov_b32 v[122:123], v[32:33], v[32:33]
	v_pk_mov_b32 v[124:125], v[32:33], v[32:33]
	v_pk_mov_b32 v[126:127], v[32:33], v[32:33]
	v_pk_mov_b32 v[128:129], v[32:33], v[32:33]
	v_pk_mov_b32 v[130:131], v[32:33], v[32:33]
	v_pk_mov_b32 v[132:133], v[32:33], v[32:33]
	v_pk_mov_b32 v[134:135], v[32:33], v[32:33]
	v_pk_mov_b32 v[136:137], v[32:33], v[32:33]
	v_pk_mov_b32 v[138:139], v[32:33], v[32:33]
	v_pk_mov_b32 v[140:141], v[32:33], v[32:33]
	v_pk_mov_b32 v[142:143], v[32:33], v[32:33]
	v_pk_mov_b32 v[144:145], v[32:33], v[32:33]
	v_pk_mov_b32 v[146:147], v[32:33], v[32:33]
	v_pk_mov_b32 v[148:149], v[32:33], v[32:33]
	v_pk_mov_b32 v[150:151], v[32:33], v[32:33]
	v_pk_mov_b32 v[152:153], v[32:33], v[32:33]
	v_pk_mov_b32 v[154:155], v[32:33], v[32:33]
	v_pk_mov_b32 v[156:157], v[32:33], v[32:33]
	v_pk_mov_b32 v[158:159], v[32:33], v[32:33]

.LBB0_661:
	s_add_u32 s20, s20, 0x58080
	s_addc_u32 s21, s21, 0
	s_add_u32 s45, s24, 0x100
	s_addc_u32 s47, s25, 0
	s_mov_b32 s48, -2
	v_mov_b32_e32 v32, 0
	v_mov_b32_e32 v33, 0
	v_pk_mov_b32 v[34:35], v[32:33], v[32:33]
	v_pk_mov_b32 v[36:37], v[32:33], v[32:33]
	v_pk_mov_b32 v[38:39], v[32:33], v[32:33]
	v_pk_mov_b32 v[40:41], v[32:33], v[32:33]
	v_pk_mov_b32 v[42:43], v[32:33], v[32:33]
	v_pk_mov_b32 v[44:45], v[32:33], v[32:33]
	v_pk_mov_b32 v[46:47], v[32:33], v[32:33]
	v_pk_mov_b32 v[48:49], v[32:33], v[32:33]
	v_pk_mov_b32 v[50:51], v[32:33], v[32:33]
	v_pk_mov_b32 v[52:53], v[32:33], v[32:33]
	v_pk_mov_b32 v[54:55], v[32:33], v[32:33]
	v_pk_mov_b32 v[56:57], v[32:33], v[32:33]
	v_pk_mov_b32 v[58:59], v[32:33], v[32:33]
	v_pk_mov_b32 v[60:61], v[32:33], v[32:33]
	v_pk_mov_b32 v[62:63], v[32:33], v[32:33]
	v_pk_mov_b32 v[64:65], v[32:33], v[32:33]
	v_pk_mov_b32 v[66:67], v[32:33], v[32:33]
	v_pk_mov_b32 v[68:69], v[32:33], v[32:33]
	v_pk_mov_b32 v[70:71], v[32:33], v[32:33]
	v_pk_mov_b32 v[72:73], v[32:33], v[32:33]
	v_pk_mov_b32 v[74:75], v[32:33], v[32:33]
	v_pk_mov_b32 v[76:77], v[32:33], v[32:33]
	v_pk_mov_b32 v[78:79], v[32:33], v[32:33]
	v_pk_mov_b32 v[80:81], v[32:33], v[32:33]
	v_pk_mov_b32 v[82:83], v[32:33], v[32:33]
	v_pk_mov_b32 v[84:85], v[32:33], v[32:33]
	v_pk_mov_b32 v[86:87], v[32:33], v[32:33]
	v_pk_mov_b32 v[88:89], v[32:33], v[32:33]
	v_pk_mov_b32 v[90:91], v[32:33], v[32:33]
	v_pk_mov_b32 v[92:93], v[32:33], v[32:33]
	v_pk_mov_b32 v[94:95], v[32:33], v[32:33]
	v_pk_mov_b32 v[96:97], v[32:33], v[32:33]
	v_pk_mov_b32 v[98:99], v[32:33], v[32:33]
	v_pk_mov_b32 v[100:101], v[32:33], v[32:33]
	v_pk_mov_b32 v[102:103], v[32:33], v[32:33]
	v_pk_mov_b32 v[104:105], v[32:33], v[32:33]
	v_pk_mov_b32 v[106:107], v[32:33], v[32:33]
	v_pk_mov_b32 v[108:109], v[32:33], v[32:33]
	v_pk_mov_b32 v[110:111], v[32:33], v[32:33]
	v_pk_mov_b32 v[112:113], v[32:33], v[32:33]
	v_pk_mov_b32 v[114:115], v[32:33], v[32:33]
	v_pk_mov_b32 v[116:117], v[32:33], v[32:33]
	v_pk_mov_b32 v[118:119], v[32:33], v[32:33]
	v_pk_mov_b32 v[120:121], v[32:33], v[32:33]
	v_pk_mov_b32 v[122:123], v[32:33], v[32:33]
	v_pk_mov_b32 v[124:125], v[32:33], v[32:33]
	v_pk_mov_b32 v[126:127], v[32:33], v[32:33]
	v_pk_mov_b32 v[128:129], v[32:33], v[32:33]
	v_pk_mov_b32 v[130:131], v[32:33], v[32:33]
	v_pk_mov_b32 v[132:133], v[32:33], v[32:33]
	v_pk_mov_b32 v[134:135], v[32:33], v[32:33]
	v_pk_mov_b32 v[136:137], v[32:33], v[32:33]
	v_pk_mov_b32 v[138:139], v[32:33], v[32:33]
	v_pk_mov_b32 v[140:141], v[32:33], v[32:33]
	v_pk_mov_b32 v[142:143], v[32:33], v[32:33]
	v_pk_mov_b32 v[144:145], v[32:33], v[32:33]
	v_pk_mov_b32 v[146:147], v[32:33], v[32:33]
	v_pk_mov_b32 v[148:149], v[32:33], v[32:33]
	v_pk_mov_b32 v[150:151], v[32:33], v[32:33]
	v_pk_mov_b32 v[152:153], v[32:33], v[32:33]
	v_pk_mov_b32 v[154:155], v[32:33], v[32:33]
	v_pk_mov_b32 v[156:157], v[32:33], v[32:33]
	v_pk_mov_b32 v[158:159], v[32:33], v[32:33]

.LBB0_791:
	s_ashr_i32 s13, s12, 31
	s_lshl_b64 s[18:19], s[12:13], 19
	s_add_u32 s18, s57, s18
	s_addc_u32 s19, s62, s19
	s_and_b64 s[20:21], s[4:5], exec
	s_cselect_b32 s13, s19, s25
	s_cselect_b32 s44, s18, s24
	s_ashr_i32 s11, s10, 31
	s_lshl_b64 s[20:21], s[10:11], 19
	v_readlane_b32 s11, v234, 51
	s_add_u32 s20, s11, s20
	v_readlane_b32 s11, v234, 52
	s_addc_u32 s21, s11, s21
	s_and_b64 s[28:29], s[4:5], exec
	s_cselect_b32 s11, s21, s27
	s_cselect_b32 s45, s20, s26
	s_add_u32 s24, s24, 0x40080
	s_addc_u32 s25, s25, 0
	s_add_u32 s47, s26, 0x100
	s_addc_u32 s48, s27, 0
	s_mov_b32 s49, -2
	v_mov_b32_e32 v0, 0
	v_mov_b32_e32 v1, 0
	v_pk_mov_b32 v[2:3], v[0:1], v[0:1]
	v_pk_mov_b32 v[4:5], v[0:1], v[0:1]
	v_pk_mov_b32 v[6:7], v[0:1], v[0:1]
	v_pk_mov_b32 v[8:9], v[0:1], v[0:1]
	v_pk_mov_b32 v[10:11], v[0:1], v[0:1]
	v_pk_mov_b32 v[12:13], v[0:1], v[0:1]
	v_pk_mov_b32 v[14:15], v[0:1], v[0:1]
	v_pk_mov_b32 v[16:17], v[0:1], v[0:1]
	v_pk_mov_b32 v[18:19], v[0:1], v[0:1]
	v_pk_mov_b32 v[20:21], v[0:1], v[0:1]
	v_pk_mov_b32 v[22:23], v[0:1], v[0:1]
	v_pk_mov_b32 v[24:25], v[0:1], v[0:1]
	v_pk_mov_b32 v[26:27], v[0:1], v[0:1]
	v_pk_mov_b32 v[28:29], v[0:1], v[0:1]
	v_pk_mov_b32 v[30:31], v[0:1], v[0:1]
	v_pk_mov_b32 v[32:33], v[0:1], v[0:1]
	v_pk_mov_b32 v[34:35], v[0:1], v[0:1]
	v_pk_mov_b32 v[36:37], v[0:1], v[0:1]
	v_pk_mov_b32 v[38:39], v[0:1], v[0:1]
	v_pk_mov_b32 v[40:41], v[0:1], v[0:1]
	v_pk_mov_b32 v[42:43], v[0:1], v[0:1]
	v_pk_mov_b32 v[44:45], v[0:1], v[0:1]
	v_pk_mov_b32 v[46:47], v[0:1], v[0:1]
	v_pk_mov_b32 v[48:49], v[0:1], v[0:1]
	v_pk_mov_b32 v[50:51], v[0:1], v[0:1]
	v_pk_mov_b32 v[52:53], v[0:1], v[0:1]
	v_pk_mov_b32 v[54:55], v[0:1], v[0:1]
	v_pk_mov_b32 v[56:57], v[0:1], v[0:1]
	v_pk_mov_b32 v[58:59], v[0:1], v[0:1]
	v_pk_mov_b32 v[60:61], v[0:1], v[0:1]
	v_pk_mov_b32 v[62:63], v[0:1], v[0:1]
	v_pk_mov_b32 v[64:65], v[0:1], v[0:1]
	v_pk_mov_b32 v[66:67], v[0:1], v[0:1]
	v_pk_mov_b32 v[68:69], v[0:1], v[0:1]
	v_pk_mov_b32 v[70:71], v[0:1], v[0:1]
	v_pk_mov_b32 v[72:73], v[0:1], v[0:1]
	v_pk_mov_b32 v[74:75], v[0:1], v[0:1]
	v_pk_mov_b32 v[76:77], v[0:1], v[0:1]
	v_pk_mov_b32 v[78:79], v[0:1], v[0:1]
	v_pk_mov_b32 v[80:81], v[0:1], v[0:1]
	v_pk_mov_b32 v[82:83], v[0:1], v[0:1]
	v_pk_mov_b32 v[84:85], v[0:1], v[0:1]
	v_pk_mov_b32 v[86:87], v[0:1], v[0:1]
	v_pk_mov_b32 v[88:89], v[0:1], v[0:1]
	v_pk_mov_b32 v[90:91], v[0:1], v[0:1]
	v_pk_mov_b32 v[92:93], v[0:1], v[0:1]
	v_pk_mov_b32 v[94:95], v[0:1], v[0:1]
	v_pk_mov_b32 v[96:97], v[0:1], v[0:1]
	v_pk_mov_b32 v[98:99], v[0:1], v[0:1]
	v_pk_mov_b32 v[100:101], v[0:1], v[0:1]
	v_pk_mov_b32 v[102:103], v[0:1], v[0:1]
	v_pk_mov_b32 v[104:105], v[0:1], v[0:1]
	v_pk_mov_b32 v[106:107], v[0:1], v[0:1]
	v_pk_mov_b32 v[108:109], v[0:1], v[0:1]
	v_pk_mov_b32 v[110:111], v[0:1], v[0:1]
	v_pk_mov_b32 v[112:113], v[0:1], v[0:1]
	v_pk_mov_b32 v[114:115], v[0:1], v[0:1]
	v_pk_mov_b32 v[116:117], v[0:1], v[0:1]
	v_pk_mov_b32 v[118:119], v[0:1], v[0:1]
	v_pk_mov_b32 v[120:121], v[0:1], v[0:1]
	v_pk_mov_b32 v[122:123], v[0:1], v[0:1]
	v_pk_mov_b32 v[124:125], v[0:1], v[0:1]
	v_pk_mov_b32 v[126:127], v[0:1], v[0:1]

.LBB0_811:
	s_ashr_i32 s13, s12, 31
	s_lshl_b64 s[18:19], s[12:13], 19
	s_add_u32 s18, s81, s18
	v_readlane_b32 s11, v234, 50
	s_addc_u32 s19, s11, s19
	s_and_b64 s[20:21], s[4:5], exec
	s_cselect_b32 s13, s19, s25
	s_cselect_b32 s44, s18, s24
	s_ashr_i32 s11, s10, 31
	s_lshl_b64 s[20:21], s[10:11], 19
	s_add_u32 s20, s57, s20
	s_addc_u32 s21, s62, s21
	s_and_b64 s[28:29], s[4:5], exec
	s_cselect_b32 s11, s21, s27
	s_cselect_b32 s45, s20, s26
	s_add_u32 s24, s24, 0x40080
	s_addc_u32 s25, s25, 0
	s_add_u32 s47, s26, 0x100
	s_addc_u32 s48, s27, 0
	s_mov_b32 s49, -2
	v_mov_b32_e32 v0, 0
	v_mov_b32_e32 v1, 0
	v_pk_mov_b32 v[2:3], v[0:1], v[0:1]
	v_pk_mov_b32 v[4:5], v[0:1], v[0:1]
	v_pk_mov_b32 v[6:7], v[0:1], v[0:1]
	v_pk_mov_b32 v[8:9], v[0:1], v[0:1]
	v_pk_mov_b32 v[10:11], v[0:1], v[0:1]
	v_pk_mov_b32 v[12:13], v[0:1], v[0:1]
	v_pk_mov_b32 v[14:15], v[0:1], v[0:1]
	v_pk_mov_b32 v[16:17], v[0:1], v[0:1]
	v_pk_mov_b32 v[18:19], v[0:1], v[0:1]
	v_pk_mov_b32 v[20:21], v[0:1], v[0:1]
	v_pk_mov_b32 v[22:23], v[0:1], v[0:1]
	v_pk_mov_b32 v[24:25], v[0:1], v[0:1]
	v_pk_mov_b32 v[26:27], v[0:1], v[0:1]
	v_pk_mov_b32 v[28:29], v[0:1], v[0:1]
	v_pk_mov_b32 v[30:31], v[0:1], v[0:1]
	v_pk_mov_b32 v[32:33], v[0:1], v[0:1]
	v_pk_mov_b32 v[34:35], v[0:1], v[0:1]
	v_pk_mov_b32 v[36:37], v[0:1], v[0:1]
	v_pk_mov_b32 v[38:39], v[0:1], v[0:1]
	v_pk_mov_b32 v[40:41], v[0:1], v[0:1]
	v_pk_mov_b32 v[42:43], v[0:1], v[0:1]
	v_pk_mov_b32 v[44:45], v[0:1], v[0:1]
	v_pk_mov_b32 v[46:47], v[0:1], v[0:1]
	v_pk_mov_b32 v[48:49], v[0:1], v[0:1]
	v_pk_mov_b32 v[50:51], v[0:1], v[0:1]
	v_pk_mov_b32 v[52:53], v[0:1], v[0:1]
	v_pk_mov_b32 v[54:55], v[0:1], v[0:1]
	v_pk_mov_b32 v[56:57], v[0:1], v[0:1]
	v_pk_mov_b32 v[58:59], v[0:1], v[0:1]
	v_pk_mov_b32 v[60:61], v[0:1], v[0:1]
	v_pk_mov_b32 v[62:63], v[0:1], v[0:1]
	v_pk_mov_b32 v[64:65], v[0:1], v[0:1]
	v_pk_mov_b32 v[66:67], v[0:1], v[0:1]
	v_pk_mov_b32 v[68:69], v[0:1], v[0:1]
	v_pk_mov_b32 v[70:71], v[0:1], v[0:1]
	v_pk_mov_b32 v[72:73], v[0:1], v[0:1]
	v_pk_mov_b32 v[74:75], v[0:1], v[0:1]
	v_pk_mov_b32 v[76:77], v[0:1], v[0:1]
	v_pk_mov_b32 v[78:79], v[0:1], v[0:1]
	v_pk_mov_b32 v[80:81], v[0:1], v[0:1]
	v_pk_mov_b32 v[82:83], v[0:1], v[0:1]
	v_pk_mov_b32 v[84:85], v[0:1], v[0:1]
	v_pk_mov_b32 v[86:87], v[0:1], v[0:1]
	v_pk_mov_b32 v[88:89], v[0:1], v[0:1]
	v_pk_mov_b32 v[90:91], v[0:1], v[0:1]
	v_pk_mov_b32 v[92:93], v[0:1], v[0:1]
	v_pk_mov_b32 v[94:95], v[0:1], v[0:1]
	v_pk_mov_b32 v[96:97], v[0:1], v[0:1]
	v_pk_mov_b32 v[98:99], v[0:1], v[0:1]
	v_pk_mov_b32 v[100:101], v[0:1], v[0:1]
	v_pk_mov_b32 v[102:103], v[0:1], v[0:1]
	v_pk_mov_b32 v[104:105], v[0:1], v[0:1]
	v_pk_mov_b32 v[106:107], v[0:1], v[0:1]
	v_pk_mov_b32 v[108:109], v[0:1], v[0:1]
	v_pk_mov_b32 v[110:111], v[0:1], v[0:1]
	v_pk_mov_b32 v[112:113], v[0:1], v[0:1]
	v_pk_mov_b32 v[114:115], v[0:1], v[0:1]
	v_pk_mov_b32 v[116:117], v[0:1], v[0:1]
	v_pk_mov_b32 v[118:119], v[0:1], v[0:1]
	v_pk_mov_b32 v[120:121], v[0:1], v[0:1]
	v_pk_mov_b32 v[122:123], v[0:1], v[0:1]
	v_pk_mov_b32 v[124:125], v[0:1], v[0:1]
	v_pk_mov_b32 v[126:127], v[0:1], v[0:1]

.LBB0_992:
	s_ashr_i32 s17, s16, 31
	s_lshl_b64 s[20:21], s[16:17], 19
	s_add_u32 s20, s68, s20
	s_addc_u32 s21, s69, s21
	s_and_b64 s[24:25], s[4:5], exec
	s_cselect_b32 s17, s21, s27
	s_cselect_b32 s50, s20, s26
	s_ashr_i32 s15, s14, 31
	s_lshl_b64 s[24:25], s[14:15], 19
	v_readlane_b32 s15, v234, 47
	s_add_u32 s24, s15, s24
	v_readlane_b32 s15, v234, 48
	s_addc_u32 s25, s15, s25
	s_and_b64 s[30:31], s[4:5], exec
	s_cselect_b32 s15, s25, s29
	s_cselect_b32 s51, s24, s28
	s_add_u32 s26, s26, 0x40080
	s_addc_u32 s27, s27, 0
	s_add_u32 s52, s28, 0x100
	s_addc_u32 s53, s29, 0
	s_mov_b32 s54, -2
	v_mov_b32_e32 v0, 0
	v_mov_b32_e32 v1, 0
	v_pk_mov_b32 v[2:3], v[0:1], v[0:1]
	v_pk_mov_b32 v[4:5], v[0:1], v[0:1]
	v_pk_mov_b32 v[6:7], v[0:1], v[0:1]
	v_pk_mov_b32 v[8:9], v[0:1], v[0:1]
	v_pk_mov_b32 v[10:11], v[0:1], v[0:1]
	v_pk_mov_b32 v[12:13], v[0:1], v[0:1]
	v_pk_mov_b32 v[14:15], v[0:1], v[0:1]
	v_pk_mov_b32 v[16:17], v[0:1], v[0:1]
	v_pk_mov_b32 v[18:19], v[0:1], v[0:1]
	v_pk_mov_b32 v[20:21], v[0:1], v[0:1]
	v_pk_mov_b32 v[22:23], v[0:1], v[0:1]
	v_pk_mov_b32 v[24:25], v[0:1], v[0:1]
	v_pk_mov_b32 v[26:27], v[0:1], v[0:1]
	v_pk_mov_b32 v[28:29], v[0:1], v[0:1]
	v_pk_mov_b32 v[30:31], v[0:1], v[0:1]
	v_pk_mov_b32 v[32:33], v[0:1], v[0:1]
	v_pk_mov_b32 v[34:35], v[0:1], v[0:1]
	v_pk_mov_b32 v[36:37], v[0:1], v[0:1]
	v_pk_mov_b32 v[38:39], v[0:1], v[0:1]
	v_pk_mov_b32 v[40:41], v[0:1], v[0:1]
	v_pk_mov_b32 v[42:43], v[0:1], v[0:1]
	v_pk_mov_b32 v[44:45], v[0:1], v[0:1]
	v_pk_mov_b32 v[46:47], v[0:1], v[0:1]
	v_pk_mov_b32 v[48:49], v[0:1], v[0:1]
	v_pk_mov_b32 v[50:51], v[0:1], v[0:1]
	v_pk_mov_b32 v[52:53], v[0:1], v[0:1]
	v_pk_mov_b32 v[54:55], v[0:1], v[0:1]
	v_pk_mov_b32 v[56:57], v[0:1], v[0:1]
	v_pk_mov_b32 v[58:59], v[0:1], v[0:1]
	v_pk_mov_b32 v[60:61], v[0:1], v[0:1]
	v_pk_mov_b32 v[62:63], v[0:1], v[0:1]
	v_pk_mov_b32 v[64:65], v[0:1], v[0:1]
	v_pk_mov_b32 v[66:67], v[0:1], v[0:1]
	v_pk_mov_b32 v[68:69], v[0:1], v[0:1]
	v_pk_mov_b32 v[70:71], v[0:1], v[0:1]
	v_pk_mov_b32 v[72:73], v[0:1], v[0:1]
	v_pk_mov_b32 v[74:75], v[0:1], v[0:1]
	v_pk_mov_b32 v[76:77], v[0:1], v[0:1]
	v_pk_mov_b32 v[78:79], v[0:1], v[0:1]
	v_pk_mov_b32 v[80:81], v[0:1], v[0:1]
	v_pk_mov_b32 v[82:83], v[0:1], v[0:1]
	v_pk_mov_b32 v[84:85], v[0:1], v[0:1]
	v_pk_mov_b32 v[86:87], v[0:1], v[0:1]
	v_pk_mov_b32 v[88:89], v[0:1], v[0:1]
	v_pk_mov_b32 v[90:91], v[0:1], v[0:1]
	v_pk_mov_b32 v[92:93], v[0:1], v[0:1]
	v_pk_mov_b32 v[94:95], v[0:1], v[0:1]
	v_pk_mov_b32 v[96:97], v[0:1], v[0:1]
	v_pk_mov_b32 v[98:99], v[0:1], v[0:1]
	v_pk_mov_b32 v[100:101], v[0:1], v[0:1]
	v_pk_mov_b32 v[102:103], v[0:1], v[0:1]
	v_pk_mov_b32 v[104:105], v[0:1], v[0:1]
	v_pk_mov_b32 v[106:107], v[0:1], v[0:1]
	v_pk_mov_b32 v[108:109], v[0:1], v[0:1]
	v_pk_mov_b32 v[110:111], v[0:1], v[0:1]
	v_pk_mov_b32 v[112:113], v[0:1], v[0:1]
	v_pk_mov_b32 v[114:115], v[0:1], v[0:1]
	v_pk_mov_b32 v[116:117], v[0:1], v[0:1]
	v_pk_mov_b32 v[118:119], v[0:1], v[0:1]
	v_pk_mov_b32 v[120:121], v[0:1], v[0:1]
	v_pk_mov_b32 v[122:123], v[0:1], v[0:1]
	v_pk_mov_b32 v[124:125], v[0:1], v[0:1]
	v_pk_mov_b32 v[126:127], v[0:1], v[0:1]

.LBB0_1271:
	s_lshl_b64 s[18:19], s[14:15], 18
	s_add_u32 s18, s68, s18
	s_addc_u32 s19, s69, s19
	s_and_b64 s[20:21], exec, s[0:1]
	s_cselect_b32 s15, s19, s29
	s_cselect_b32 s57, s18, s28
	s_ashr_i32 s17, s16, 31
	s_lshl_b64 s[20:21], s[16:17], 18
	s_add_u32 s20, s76, s20
	s_addc_u32 s21, s77, s21
	s_and_b64 s[34:35], exec, s[0:1]
	s_cselect_b32 s17, s21, s31
	s_cselect_b32 s62, s20, s30
	s_add_u32 s28, s28, 0x20080
	s_addc_u32 s29, s29, 0
	s_add_u32 s63, s30, 0x100
	s_addc_u32 s64, s31, 0
	s_mov_b32 s65, -2
	v_mov_b32_e32 v32, 0
	v_mov_b32_e32 v33, 0
	v_pk_mov_b32 v[34:35], v[32:33], v[32:33]
	v_pk_mov_b32 v[36:37], v[32:33], v[32:33]
	v_pk_mov_b32 v[38:39], v[32:33], v[32:33]
	v_pk_mov_b32 v[40:41], v[32:33], v[32:33]
	v_pk_mov_b32 v[42:43], v[32:33], v[32:33]
	v_pk_mov_b32 v[44:45], v[32:33], v[32:33]
	v_pk_mov_b32 v[46:47], v[32:33], v[32:33]
	v_pk_mov_b32 v[48:49], v[32:33], v[32:33]
	v_pk_mov_b32 v[50:51], v[32:33], v[32:33]
	v_pk_mov_b32 v[52:53], v[32:33], v[32:33]
	v_pk_mov_b32 v[54:55], v[32:33], v[32:33]
	v_pk_mov_b32 v[56:57], v[32:33], v[32:33]
	v_pk_mov_b32 v[58:59], v[32:33], v[32:33]
	v_pk_mov_b32 v[60:61], v[32:33], v[32:33]
	v_pk_mov_b32 v[62:63], v[32:33], v[32:33]
	v_pk_mov_b32 v[64:65], v[32:33], v[32:33]
	v_pk_mov_b32 v[66:67], v[32:33], v[32:33]
	v_pk_mov_b32 v[68:69], v[32:33], v[32:33]
	v_pk_mov_b32 v[70:71], v[32:33], v[32:33]
	v_pk_mov_b32 v[72:73], v[32:33], v[32:33]
	v_pk_mov_b32 v[74:75], v[32:33], v[32:33]
	v_pk_mov_b32 v[76:77], v[32:33], v[32:33]
	v_pk_mov_b32 v[78:79], v[32:33], v[32:33]
	v_pk_mov_b32 v[80:81], v[32:33], v[32:33]
	v_pk_mov_b32 v[82:83], v[32:33], v[32:33]
	v_pk_mov_b32 v[84:85], v[32:33], v[32:33]
	v_pk_mov_b32 v[86:87], v[32:33], v[32:33]
	v_pk_mov_b32 v[88:89], v[32:33], v[32:33]
	v_pk_mov_b32 v[90:91], v[32:33], v[32:33]
	v_pk_mov_b32 v[92:93], v[32:33], v[32:33]
	v_pk_mov_b32 v[94:95], v[32:33], v[32:33]
	v_pk_mov_b32 v[96:97], v[32:33], v[32:33]
	v_pk_mov_b32 v[98:99], v[32:33], v[32:33]
	v_pk_mov_b32 v[100:101], v[32:33], v[32:33]
	v_pk_mov_b32 v[102:103], v[32:33], v[32:33]
	v_pk_mov_b32 v[104:105], v[32:33], v[32:33]
	v_pk_mov_b32 v[106:107], v[32:33], v[32:33]
	v_pk_mov_b32 v[108:109], v[32:33], v[32:33]
	v_pk_mov_b32 v[110:111], v[32:33], v[32:33]
	v_pk_mov_b32 v[112:113], v[32:33], v[32:33]
	v_pk_mov_b32 v[114:115], v[32:33], v[32:33]
	v_pk_mov_b32 v[116:117], v[32:33], v[32:33]
	v_pk_mov_b32 v[118:119], v[32:33], v[32:33]
	v_pk_mov_b32 v[120:121], v[32:33], v[32:33]
	v_pk_mov_b32 v[122:123], v[32:33], v[32:33]
	v_pk_mov_b32 v[124:125], v[32:33], v[32:33]
	v_pk_mov_b32 v[126:127], v[32:33], v[32:33]
	v_pk_mov_b32 v[128:129], v[32:33], v[32:33]
	v_pk_mov_b32 v[130:131], v[32:33], v[32:33]
	v_pk_mov_b32 v[132:133], v[32:33], v[32:33]
	v_pk_mov_b32 v[134:135], v[32:33], v[32:33]
	v_pk_mov_b32 v[136:137], v[32:33], v[32:33]
	v_pk_mov_b32 v[138:139], v[32:33], v[32:33]
	v_pk_mov_b32 v[140:141], v[32:33], v[32:33]
	v_pk_mov_b32 v[142:143], v[32:33], v[32:33]
	v_pk_mov_b32 v[144:145], v[32:33], v[32:33]
	v_pk_mov_b32 v[146:147], v[32:33], v[32:33]
	v_pk_mov_b32 v[148:149], v[32:33], v[32:33]
	v_pk_mov_b32 v[150:151], v[32:33], v[32:33]
	v_pk_mov_b32 v[152:153], v[32:33], v[32:33]
	v_pk_mov_b32 v[154:155], v[32:33], v[32:33]
	v_pk_mov_b32 v[156:157], v[32:33], v[32:33]
	v_pk_mov_b32 v[158:159], v[32:33], v[32:33]

.LBB0_1348:
	s_add_u32 s30, s30, 0x70080
	s_addc_u32 s31, s31, 0
	s_add_u32 s72, s34, 0x100
	s_addc_u32 s73, s35, 0
	s_mov_b32 s74, -2
	v_mov_b32_e32 v32, 0
	v_mov_b32_e32 v33, 0
	v_pk_mov_b32 v[34:35], v[32:33], v[32:33]
	v_pk_mov_b32 v[36:37], v[32:33], v[32:33]
	v_pk_mov_b32 v[38:39], v[32:33], v[32:33]
	v_pk_mov_b32 v[40:41], v[32:33], v[32:33]
	v_pk_mov_b32 v[42:43], v[32:33], v[32:33]
	v_pk_mov_b32 v[44:45], v[32:33], v[32:33]
	v_pk_mov_b32 v[46:47], v[32:33], v[32:33]
	v_pk_mov_b32 v[48:49], v[32:33], v[32:33]
	v_pk_mov_b32 v[50:51], v[32:33], v[32:33]
	v_pk_mov_b32 v[52:53], v[32:33], v[32:33]
	v_pk_mov_b32 v[54:55], v[32:33], v[32:33]
	v_pk_mov_b32 v[56:57], v[32:33], v[32:33]
	v_pk_mov_b32 v[58:59], v[32:33], v[32:33]
	v_pk_mov_b32 v[60:61], v[32:33], v[32:33]
	v_pk_mov_b32 v[62:63], v[32:33], v[32:33]
	v_pk_mov_b32 v[64:65], v[32:33], v[32:33]
	v_pk_mov_b32 v[66:67], v[32:33], v[32:33]
	v_pk_mov_b32 v[68:69], v[32:33], v[32:33]
	v_pk_mov_b32 v[70:71], v[32:33], v[32:33]
	v_pk_mov_b32 v[72:73], v[32:33], v[32:33]
	v_pk_mov_b32 v[74:75], v[32:33], v[32:33]
	v_pk_mov_b32 v[76:77], v[32:33], v[32:33]
	v_pk_mov_b32 v[78:79], v[32:33], v[32:33]
	v_pk_mov_b32 v[80:81], v[32:33], v[32:33]
	v_pk_mov_b32 v[82:83], v[32:33], v[32:33]
	v_pk_mov_b32 v[84:85], v[32:33], v[32:33]
	v_pk_mov_b32 v[86:87], v[32:33], v[32:33]
	v_pk_mov_b32 v[88:89], v[32:33], v[32:33]
	v_pk_mov_b32 v[90:91], v[32:33], v[32:33]
	v_pk_mov_b32 v[92:93], v[32:33], v[32:33]
	v_pk_mov_b32 v[94:95], v[32:33], v[32:33]
	v_pk_mov_b32 v[96:97], v[32:33], v[32:33]
	v_pk_mov_b32 v[98:99], v[32:33], v[32:33]
	v_pk_mov_b32 v[100:101], v[32:33], v[32:33]
	v_pk_mov_b32 v[102:103], v[32:33], v[32:33]
	v_pk_mov_b32 v[104:105], v[32:33], v[32:33]
	v_pk_mov_b32 v[106:107], v[32:33], v[32:33]
	v_pk_mov_b32 v[108:109], v[32:33], v[32:33]
	v_pk_mov_b32 v[110:111], v[32:33], v[32:33]
	v_pk_mov_b32 v[112:113], v[32:33], v[32:33]
	v_pk_mov_b32 v[114:115], v[32:33], v[32:33]
	v_pk_mov_b32 v[116:117], v[32:33], v[32:33]
	v_pk_mov_b32 v[118:119], v[32:33], v[32:33]
	v_pk_mov_b32 v[120:121], v[32:33], v[32:33]
	v_pk_mov_b32 v[122:123], v[32:33], v[32:33]
	v_pk_mov_b32 v[124:125], v[32:33], v[32:33]
	v_pk_mov_b32 v[126:127], v[32:33], v[32:33]
	v_pk_mov_b32 v[128:129], v[32:33], v[32:33]
	v_pk_mov_b32 v[130:131], v[32:33], v[32:33]
	v_pk_mov_b32 v[132:133], v[32:33], v[32:33]
	v_pk_mov_b32 v[134:135], v[32:33], v[32:33]
	v_pk_mov_b32 v[136:137], v[32:33], v[32:33]
	v_pk_mov_b32 v[138:139], v[32:33], v[32:33]
	v_pk_mov_b32 v[140:141], v[32:33], v[32:33]
	v_pk_mov_b32 v[142:143], v[32:33], v[32:33]
	v_pk_mov_b32 v[144:145], v[32:33], v[32:33]
	v_pk_mov_b32 v[146:147], v[32:33], v[32:33]
	v_pk_mov_b32 v[148:149], v[32:33], v[32:33]
	v_pk_mov_b32 v[150:151], v[32:33], v[32:33]
	v_pk_mov_b32 v[152:153], v[32:33], v[32:33]
	v_pk_mov_b32 v[154:155], v[32:33], v[32:33]
	v_pk_mov_b32 v[156:157], v[32:33], v[32:33]
	v_pk_mov_b32 v[158:159], v[32:33], v[32:33]
